# hand-written SwiGLU-in epilogue for both FFN-in GEMMs (packed scale multiply, one 32-bit address add per store, same op order); no s_setprio around MFMA blocks
# baseline (speedup 1.0000x reference)
; __device__ __forceinline__ float ex2(float x) { return __builtin_amdgcn_exp2f(x); }
; __device__ __forceinline__ u32x4 pack8(const f32x4 a, const f32x4 b) { u32x4 w; w.x = pk2(a[0], a[1]); w.y = pk2(a[2], a[3]); w.z = pk2(b[0], b[1]); w.w = pk2(b[2], b[3]); return w; }
;     __device__ __forceinline__ bool operator()(EPI_ARGS) const {
; #pragma unroll
;         for (int ai = 0; ai < 2; ++ai)
; #pragma unroll
;             for (int m = 0; m < 4; ++m) {
;                 const size_t row = (size_t)u.pm * 256 + ROWLOC(ai, m);
;                 const f32x4 a0 = acc[ai][0][m][0], a1 = acc[ai][0][m][1], b0 = acc[ai][1][m][0], b1 = acc[ai][1][m][1];
;                 const f32x4 t0 = a0 * (-1.4426950409f), t1 = a1 * (-1.4426950409f);
;                 f32x4 d0, d1;
; #pragma unroll
;                 for (int e = 0; e < 4; ++e) { d0[e] = ex2(t0[e]); d1[e] = ex2(t1[e]); }
;                 d0 = d0 + 1.0f; d1 = d1 + 1.0f;
;                 f32x4 r0, r1;
; #pragma unroll
;                 for (int e = 0; e < 4; ++e) { r0[e] = __builtin_amdgcn_rcpf(d0[e]); r1[e] = __builtin_amdgcn_rcpf(d1[e]); }
;                 const f32x4 o0 = (a0 * b0) * r0, o1 = (a1 * b1) * r1;
;                 *(u32x4*)(act + row * DFF + u.pn * 128 + 32 * wc + 8 * fq) = pack8(o0, o1);
;             }
;         return false;
;     }
.LBB0_313:
	s_lshl_b32 s38, s22, 8
	s_lshl_b32 s40, s61, 8
	v_add_u32_e32 v148, s38, v136
	s_add_i32 s40, s40, s10
	v_add_u32_e32 v148, s48, v148
	v_lshl_add_u32 v149, v137, 4, s40
	v_mul_u32_u24_e32 v148, 0x1600, v148
	v_mov_b32_e32 v152, 0xbfb8aa3b
	v_mov_b32_e32 v153, 0xbfb8aa3b
	v_add_u32_e32 v148, v148, v149
	v_pk_mul_f32 v[144:145], v[124:125], v[152:153]
	v_pk_mul_f32 v[146:147], v[126:127], v[152:153]
	v_exp_f32_e32 v144, v144
	v_exp_f32_e32 v145, v145
	v_exp_f32_e32 v146, v146
	v_exp_f32_e32 v147, v147
	v_pk_mul_f32 v[116:117], v[124:125], v[116:117]
	v_pk_mul_f32 v[118:119], v[126:127], v[118:119]
	v_pk_add_f32 v[144:145], v[144:145], 1.0 op_sel_hi:[1,0]
	v_pk_add_f32 v[146:147], v[146:147], 1.0 op_sel_hi:[1,0]
	v_rcp_f32_e32 v144, v144
	v_rcp_f32_e32 v145, v145
	v_rcp_f32_e32 v146, v146
	v_rcp_f32_e32 v147, v147
	v_pk_mul_f32 v[116:117], v[144:145], v[116:117]
	v_pk_mul_f32 v[118:119], v[146:147], v[118:119]
	v_cvt_pk_bf16_f32 v124, v116, v117
	v_cvt_pk_bf16_f32 v125, v118, v119
	v_pk_mul_f32 v[144:145], v[120:121], v[152:153]
	v_pk_mul_f32 v[146:147], v[122:123], v[152:153]
	v_exp_f32_e32 v144, v144
	v_exp_f32_e32 v145, v145
	v_exp_f32_e32 v146, v146
	v_exp_f32_e32 v147, v147
	v_pk_mul_f32 v[112:113], v[120:121], v[112:113]
	v_pk_mul_f32 v[114:115], v[122:123], v[114:115]
	v_pk_add_f32 v[144:145], v[144:145], 1.0 op_sel_hi:[1,0]
	v_pk_add_f32 v[146:147], v[146:147], 1.0 op_sel_hi:[1,0]
	v_rcp_f32_e32 v144, v144
	v_rcp_f32_e32 v145, v145
	v_rcp_f32_e32 v146, v146
	v_rcp_f32_e32 v147, v147
	v_pk_mul_f32 v[112:113], v[144:145], v[112:113]
	v_pk_mul_f32 v[114:115], v[146:147], v[114:115]
	v_cvt_pk_bf16_f32 v126, v112, v113
	v_cvt_pk_bf16_f32 v127, v114, v115
	global_store_dwordx4 v148, v[124:127], s[16:17]
	v_pk_mul_f32 v[144:145], v[108:109], v[152:153]
	v_pk_mul_f32 v[146:147], v[110:111], v[152:153]
	v_exp_f32_e32 v144, v144
	v_exp_f32_e32 v145, v145
	v_exp_f32_e32 v146, v146
	v_exp_f32_e32 v147, v147
	v_pk_mul_f32 v[100:101], v[108:109], v[100:101]
	v_pk_mul_f32 v[102:103], v[110:111], v[102:103]
	v_pk_add_f32 v[144:145], v[144:145], 1.0 op_sel_hi:[1,0]
	v_pk_add_f32 v[146:147], v[146:147], 1.0 op_sel_hi:[1,0]
	v_rcp_f32_e32 v144, v144
	v_rcp_f32_e32 v145, v145
	v_rcp_f32_e32 v146, v146
	v_rcp_f32_e32 v147, v147
	v_pk_mul_f32 v[100:101], v[144:145], v[100:101]
	v_pk_mul_f32 v[102:103], v[146:147], v[102:103]
	v_cvt_pk_bf16_f32 v108, v100, v101
	v_cvt_pk_bf16_f32 v109, v102, v103
	v_pk_mul_f32 v[144:145], v[104:105], v[152:153]
	v_pk_mul_f32 v[146:147], v[106:107], v[152:153]
	v_exp_f32_e32 v144, v144
	v_exp_f32_e32 v145, v145
	v_exp_f32_e32 v146, v146
	v_exp_f32_e32 v147, v147
	v_pk_mul_f32 v[96:97], v[104:105], v[96:97]
	v_pk_mul_f32 v[98:99], v[106:107], v[98:99]
	v_pk_add_f32 v[144:145], v[144:145], 1.0 op_sel_hi:[1,0]
	v_pk_add_f32 v[146:147], v[146:147], 1.0 op_sel_hi:[1,0]
	v_rcp_f32_e32 v144, v144
	v_rcp_f32_e32 v145, v145
	v_rcp_f32_e32 v146, v146
	v_rcp_f32_e32 v147, v147
	v_pk_mul_f32 v[96:97], v[144:145], v[96:97]
	v_pk_mul_f32 v[98:99], v[146:147], v[98:99]
	v_cvt_pk_bf16_f32 v110, v96, v97
	v_cvt_pk_bf16_f32 v111, v98, v99
	v_add_u32_e32 v150, 0x16000, v148
	global_store_dwordx4 v150, v[108:111], s[16:17]
	v_pk_mul_f32 v[144:145], v[92:93], v[152:153]
	v_pk_mul_f32 v[146:147], v[94:95], v[152:153]
	v_exp_f32_e32 v144, v144
	v_exp_f32_e32 v145, v145
	v_exp_f32_e32 v146, v146
	v_exp_f32_e32 v147, v147
	v_pk_mul_f32 v[84:85], v[92:93], v[84:85]
	v_pk_mul_f32 v[86:87], v[94:95], v[86:87]
	v_pk_add_f32 v[144:145], v[144:145], 1.0 op_sel_hi:[1,0]
	v_pk_add_f32 v[146:147], v[146:147], 1.0 op_sel_hi:[1,0]
	v_rcp_f32_e32 v144, v144
	v_rcp_f32_e32 v145, v145
	v_rcp_f32_e32 v146, v146
	v_rcp_f32_e32 v147, v147
	v_pk_mul_f32 v[84:85], v[144:145], v[84:85]
	v_pk_mul_f32 v[86:87], v[146:147], v[86:87]
	v_cvt_pk_bf16_f32 v92, v84, v85
	v_cvt_pk_bf16_f32 v93, v86, v87
	v_pk_mul_f32 v[144:145], v[88:89], v[152:153]
	v_pk_mul_f32 v[146:147], v[90:91], v[152:153]
	v_exp_f32_e32 v144, v144
	v_exp_f32_e32 v145, v145
	v_exp_f32_e32 v146, v146
	v_exp_f32_e32 v147, v147
	v_pk_mul_f32 v[80:81], v[88:89], v[80:81]
	v_pk_mul_f32 v[82:83], v[90:91], v[82:83]
	v_pk_add_f32 v[144:145], v[144:145], 1.0 op_sel_hi:[1,0]
	v_pk_add_f32 v[146:147], v[146:147], 1.0 op_sel_hi:[1,0]
	v_rcp_f32_e32 v144, v144
	v_rcp_f32_e32 v145, v145
	v_rcp_f32_e32 v146, v146
	v_rcp_f32_e32 v147, v147
	v_pk_mul_f32 v[80:81], v[144:145], v[80:81]
	v_pk_mul_f32 v[82:83], v[146:147], v[82:83]
	v_cvt_pk_bf16_f32 v94, v80, v81
	v_cvt_pk_bf16_f32 v95, v82, v83
	v_add_u32_e32 v150, 0x2c000, v148
	global_store_dwordx4 v150, v[92:95], s[16:17]
	v_pk_mul_f32 v[144:145], v[76:77], v[152:153]
	v_pk_mul_f32 v[146:147], v[78:79], v[152:153]
	v_exp_f32_e32 v144, v144
	v_exp_f32_e32 v145, v145
	v_exp_f32_e32 v146, v146
	v_exp_f32_e32 v147, v147
	v_pk_mul_f32 v[68:69], v[76:77], v[68:69]
	v_pk_mul_f32 v[70:71], v[78:79], v[70:71]
	v_pk_add_f32 v[144:145], v[144:145], 1.0 op_sel_hi:[1,0]
	v_pk_add_f32 v[146:147], v[146:147], 1.0 op_sel_hi:[1,0]
	v_rcp_f32_e32 v144, v144
	v_rcp_f32_e32 v145, v145
	v_rcp_f32_e32 v146, v146
	v_rcp_f32_e32 v147, v147
	v_pk_mul_f32 v[68:69], v[144:145], v[68:69]
	v_pk_mul_f32 v[70:71], v[146:147], v[70:71]
	v_cvt_pk_bf16_f32 v76, v68, v69
	v_cvt_pk_bf16_f32 v77, v70, v71
	v_pk_mul_f32 v[144:145], v[72:73], v[152:153]
	v_pk_mul_f32 v[146:147], v[74:75], v[152:153]
	v_exp_f32_e32 v144, v144
	v_exp_f32_e32 v145, v145
	v_exp_f32_e32 v146, v146
	v_exp_f32_e32 v147, v147
	v_pk_mul_f32 v[64:65], v[72:73], v[64:65]
	v_pk_mul_f32 v[66:67], v[74:75], v[66:67]
	v_pk_add_f32 v[144:145], v[144:145], 1.0 op_sel_hi:[1,0]
	v_pk_add_f32 v[146:147], v[146:147], 1.0 op_sel_hi:[1,0]
; __device__ __forceinline__ float ex2(float x) { return __builtin_amdgcn_exp2f(x); }
; __device__ __forceinline__ u32x4 pack8(const f32x4 a, const f32x4 b) { u32x4 w; w.x = pk2(a[0], a[1]); w.y = pk2(a[2], a[3]); w.z = pk2(b[0], b[1]); w.w = pk2(b[2], b[3]); return w; }
;     __device__ __forceinline__ bool operator()(EPI_ARGS) const {
;     ...
;                 const size_t row = (size_t)u.pm * 256 + ROWLOC(ai, m);
;                 const f32x4 a0 = acc[ai][0][m][0], a1 = acc[ai][0][m][1], b0 = acc[ai][1][m][0], b1 = acc[ai][1][m][1];
;                 const f32x4 t0 = a0 * (-1.4426950409f), t1 = a1 * (-1.4426950409f);
;                 f32x4 d0, d1;
; #pragma unroll
;                 for (int e = 0; e < 4; ++e) { d0[e] = ex2(t0[e]); d1[e] = ex2(t1[e]); }
;                 d0 = d0 + 1.0f; d1 = d1 + 1.0f;
;                 f32x4 r0, r1;
; #pragma unroll
;                 for (int e = 0; e < 4; ++e) { r0[e] = __builtin_amdgcn_rcpf(d0[e]); r1[e] = __builtin_amdgcn_rcpf(d1[e]); }
;                 const f32x4 o0 = (a0 * b0) * r0, o1 = (a1 * b1) * r1;
;                 *(u32x4*)(act + row * DFF + u.pn * 128 + 32 * wc + 8 * fq) = pack8(o0, o1);
;             }
;         return false;
	v_rcp_f32_e32 v144, v144
	v_rcp_f32_e32 v145, v145
	v_rcp_f32_e32 v146, v146
	v_rcp_f32_e32 v147, v147
	v_pk_mul_f32 v[64:65], v[144:145], v[64:65]
	v_pk_mul_f32 v[66:67], v[146:147], v[66:67]
	v_cvt_pk_bf16_f32 v78, v64, v65
	v_cvt_pk_bf16_f32 v79, v66, v67
	v_add_u32_e32 v150, 0x42000, v148
	global_store_dwordx4 v150, v[76:79], s[16:17]
	v_pk_mul_f32 v[144:145], v[60:61], v[152:153]
	v_pk_mul_f32 v[146:147], v[62:63], v[152:153]
	v_exp_f32_e32 v144, v144
	v_exp_f32_e32 v145, v145
	v_exp_f32_e32 v146, v146
	v_exp_f32_e32 v147, v147
	v_pk_mul_f32 v[52:53], v[60:61], v[52:53]
	v_pk_mul_f32 v[54:55], v[62:63], v[54:55]
	v_pk_add_f32 v[144:145], v[144:145], 1.0 op_sel_hi:[1,0]
	v_pk_add_f32 v[146:147], v[146:147], 1.0 op_sel_hi:[1,0]
	v_rcp_f32_e32 v144, v144
	v_rcp_f32_e32 v145, v145
	v_rcp_f32_e32 v146, v146
	v_rcp_f32_e32 v147, v147
	v_pk_mul_f32 v[52:53], v[144:145], v[52:53]
	v_pk_mul_f32 v[54:55], v[146:147], v[54:55]
	v_cvt_pk_bf16_f32 v60, v52, v53
	v_cvt_pk_bf16_f32 v61, v54, v55
	v_pk_mul_f32 v[144:145], v[56:57], v[152:153]
	v_pk_mul_f32 v[146:147], v[58:59], v[152:153]
	v_exp_f32_e32 v144, v144
	v_exp_f32_e32 v145, v145
	v_exp_f32_e32 v146, v146
	v_exp_f32_e32 v147, v147
	v_pk_mul_f32 v[48:49], v[56:57], v[48:49]
	v_pk_mul_f32 v[50:51], v[58:59], v[50:51]
	v_pk_add_f32 v[144:145], v[144:145], 1.0 op_sel_hi:[1,0]
	v_pk_add_f32 v[146:147], v[146:147], 1.0 op_sel_hi:[1,0]
	v_rcp_f32_e32 v144, v144
	v_rcp_f32_e32 v145, v145
	v_rcp_f32_e32 v146, v146
	v_rcp_f32_e32 v147, v147
	v_pk_mul_f32 v[48:49], v[144:145], v[48:49]
	v_pk_mul_f32 v[50:51], v[146:147], v[50:51]
	v_cvt_pk_bf16_f32 v62, v48, v49
	v_cvt_pk_bf16_f32 v63, v50, v51
	v_add_u32_e32 v150, 0xb0000, v148
	global_store_dwordx4 v150, v[60:63], s[16:17]
	v_pk_mul_f32 v[144:145], v[44:45], v[152:153]
	v_pk_mul_f32 v[146:147], v[46:47], v[152:153]
	v_exp_f32_e32 v144, v144
	v_exp_f32_e32 v145, v145
	v_exp_f32_e32 v146, v146
	v_exp_f32_e32 v147, v147
	v_pk_mul_f32 v[36:37], v[44:45], v[36:37]
	v_pk_mul_f32 v[38:39], v[46:47], v[38:39]
	v_pk_add_f32 v[144:145], v[144:145], 1.0 op_sel_hi:[1,0]
	v_pk_add_f32 v[146:147], v[146:147], 1.0 op_sel_hi:[1,0]
	v_rcp_f32_e32 v144, v144
	v_rcp_f32_e32 v145, v145
	v_rcp_f32_e32 v146, v146
	v_rcp_f32_e32 v147, v147
	v_pk_mul_f32 v[36:37], v[144:145], v[36:37]
	v_pk_mul_f32 v[38:39], v[146:147], v[38:39]
	v_cvt_pk_bf16_f32 v44, v36, v37
	v_cvt_pk_bf16_f32 v45, v38, v39
	v_pk_mul_f32 v[144:145], v[40:41], v[152:153]
	v_pk_mul_f32 v[146:147], v[42:43], v[152:153]
	v_exp_f32_e32 v144, v144
	v_exp_f32_e32 v145, v145
	v_exp_f32_e32 v146, v146
	v_exp_f32_e32 v147, v147
	v_pk_mul_f32 v[32:33], v[40:41], v[32:33]
	v_pk_mul_f32 v[34:35], v[42:43], v[34:35]
	v_pk_add_f32 v[144:145], v[144:145], 1.0 op_sel_hi:[1,0]
	v_pk_add_f32 v[146:147], v[146:147], 1.0 op_sel_hi:[1,0]
	v_rcp_f32_e32 v144, v144
	v_rcp_f32_e32 v145, v145
	v_rcp_f32_e32 v146, v146
	v_rcp_f32_e32 v147, v147
	v_pk_mul_f32 v[32:33], v[144:145], v[32:33]
	v_pk_mul_f32 v[34:35], v[146:147], v[34:35]
	v_cvt_pk_bf16_f32 v46, v32, v33
	v_cvt_pk_bf16_f32 v47, v34, v35
	v_add_u32_e32 v150, 0xc6000, v148
	global_store_dwordx4 v150, v[44:47], s[16:17]
	v_pk_mul_f32 v[144:145], v[28:29], v[152:153]
	v_pk_mul_f32 v[146:147], v[30:31], v[152:153]
	v_exp_f32_e32 v144, v144
	v_exp_f32_e32 v145, v145
	v_exp_f32_e32 v146, v146
	v_exp_f32_e32 v147, v147
	v_pk_mul_f32 v[20:21], v[28:29], v[20:21]
	v_pk_mul_f32 v[22:23], v[30:31], v[22:23]
	v_pk_add_f32 v[144:145], v[144:145], 1.0 op_sel_hi:[1,0]
	v_pk_add_f32 v[146:147], v[146:147], 1.0 op_sel_hi:[1,0]
	v_rcp_f32_e32 v144, v144
	v_rcp_f32_e32 v145, v145
	v_rcp_f32_e32 v146, v146
	v_rcp_f32_e32 v147, v147
	v_pk_mul_f32 v[20:21], v[144:145], v[20:21]
	v_pk_mul_f32 v[22:23], v[146:147], v[22:23]
	v_cvt_pk_bf16_f32 v28, v20, v21
	v_cvt_pk_bf16_f32 v29, v22, v23
	v_pk_mul_f32 v[144:145], v[24:25], v[152:153]
	v_pk_mul_f32 v[146:147], v[26:27], v[152:153]
	v_exp_f32_e32 v144, v144
	v_exp_f32_e32 v145, v145
	v_exp_f32_e32 v146, v146
	v_exp_f32_e32 v147, v147
	v_pk_mul_f32 v[16:17], v[24:25], v[16:17]
	v_pk_mul_f32 v[18:19], v[26:27], v[18:19]
	v_pk_add_f32 v[144:145], v[144:145], 1.0 op_sel_hi:[1,0]
	v_pk_add_f32 v[146:147], v[146:147], 1.0 op_sel_hi:[1,0]
	v_rcp_f32_e32 v144, v144
	v_rcp_f32_e32 v145, v145
	v_rcp_f32_e32 v146, v146
	v_rcp_f32_e32 v147, v147
	v_pk_mul_f32 v[16:17], v[144:145], v[16:17]
	v_pk_mul_f32 v[18:19], v[146:147], v[18:19]
	v_cvt_pk_bf16_f32 v30, v16, v17
	v_cvt_pk_bf16_f32 v31, v18, v19
	v_add_u32_e32 v150, 0xdc000, v148
	global_store_dwordx4 v150, v[28:31], s[16:17]
	v_pk_mul_f32 v[144:145], v[12:13], v[152:153]
	v_pk_mul_f32 v[146:147], v[14:15], v[152:153]
	v_exp_f32_e32 v144, v144
	v_exp_f32_e32 v145, v145
	v_exp_f32_e32 v146, v146
	v_exp_f32_e32 v147, v147
	v_pk_mul_f32 v[4:5], v[12:13], v[4:5]
	v_pk_mul_f32 v[6:7], v[14:15], v[6:7]
	v_pk_add_f32 v[144:145], v[144:145], 1.0 op_sel_hi:[1,0]
	v_pk_add_f32 v[146:147], v[146:147], 1.0 op_sel_hi:[1,0]
	v_rcp_f32_e32 v144, v144
	v_rcp_f32_e32 v145, v145
	v_rcp_f32_e32 v146, v146
	v_rcp_f32_e32 v147, v147
	v_pk_mul_f32 v[4:5], v[144:145], v[4:5]
	v_pk_mul_f32 v[6:7], v[146:147], v[6:7]
	v_cvt_pk_bf16_f32 v12, v4, v5
	v_cvt_pk_bf16_f32 v13, v6, v7
	v_pk_mul_f32 v[144:145], v[8:9], v[152:153]
	v_pk_mul_f32 v[146:147], v[10:11], v[152:153]
	v_exp_f32_e32 v144, v144
	v_exp_f32_e32 v145, v145
	v_exp_f32_e32 v146, v146
	v_exp_f32_e32 v147, v147
	v_pk_mul_f32 v[0:1], v[8:9], v[0:1]
	v_pk_mul_f32 v[2:3], v[10:11], v[2:3]
	v_pk_add_f32 v[144:145], v[144:145], 1.0 op_sel_hi:[1,0]
	v_pk_add_f32 v[146:147], v[146:147], 1.0 op_sel_hi:[1,0]
	v_rcp_f32_e32 v144, v144
	v_rcp_f32_e32 v145, v145
	v_rcp_f32_e32 v146, v146
	v_rcp_f32_e32 v147, v147
	v_pk_mul_f32 v[0:1], v[144:145], v[0:1]
	v_pk_mul_f32 v[2:3], v[146:147], v[2:3]
	v_cvt_pk_bf16_f32 v14, v0, v1
	v_cvt_pk_bf16_f32 v15, v2, v3
	v_add_u32_e32 v150, 0xf2000, v148
	global_store_dwordx4 v150, v[12:15], s[16:17]
	s_andn2_b64 vcc, exec, s[6:7]
	s_mov_b64 s[6:7], -1
	s_cbranch_vccnz .LBB0_296
	s_andn2_b64 vcc, exec, s[14:15]
	s_cbranch_vccnz .LBB0_295
	s_barrier
	s_branch .LBB0_295

; __device__ __forceinline__ float ex2(float x) { return __builtin_amdgcn_exp2f(x); }
; __device__ __forceinline__ u32x4 pack8(const f32x4 a, const f32x4 b) { u32x4 w; w.x = pk2(a[0], a[1]); w.y = pk2(a[2], a[3]); w.z = pk2(b[0], b[1]); w.w = pk2(b[2], b[3]); return w; }
;     __device__ __forceinline__ bool operator()(EPI_ARGS) const {
; #pragma unroll
;         for (int ai = 0; ai < 2; ++ai)
; #pragma unroll
;             for (int m = 0; m < 4; ++m) {
;                 const size_t row = (size_t)u.pm * 256 + ROWLOC(ai, m);
;                 const f32x4 a0 = acc[ai][0][m][0], a1 = acc[ai][0][m][1], b0 = acc[ai][1][m][0], b1 = acc[ai][1][m][1];
;                 const f32x4 t0 = a0 * (-1.4426950409f), t1 = a1 * (-1.4426950409f);
;                 f32x4 d0, d1;
; #pragma unroll
;                 for (int e = 0; e < 4; ++e) { d0[e] = ex2(t0[e]); d1[e] = ex2(t1[e]); }
;                 d0 = d0 + 1.0f; d1 = d1 + 1.0f;
;                 f32x4 r0, r1;
; #pragma unroll
;                 for (int e = 0; e < 4; ++e) { r0[e] = __builtin_amdgcn_rcpf(d0[e]); r1[e] = __builtin_amdgcn_rcpf(d1[e]); }
;                 const f32x4 o0 = (a0 * b0) * r0, o1 = (a1 * b1) * r1;
;                 *(u32x4*)(act + row * DFF + u.pn * 128 + 32 * wc + 8 * fq) = pack8(o0, o1);
;             }
;         return false;
;     }
.LBB0_1490:
	s_lshl_b32 s24, s18, 8
	s_lshl_b32 s26, s58, 8
	v_add_u32_e32 v148, s24, v136
	s_add_i32 s26, s26, s6
	v_add_u32_e32 v148, s47, v148
	v_lshl_add_u32 v149, v137, 4, s26
	v_mul_u32_u24_e32 v148, 0x1600, v148
	v_mov_b32_e32 v152, 0xbfb8aa3b
	v_mov_b32_e32 v153, 0xbfb8aa3b
	v_add_u32_e32 v148, v148, v149
	v_pk_mul_f32 v[144:145], v[124:125], v[152:153]
	v_pk_mul_f32 v[146:147], v[126:127], v[152:153]
	v_exp_f32_e32 v144, v144
	v_exp_f32_e32 v145, v145
	v_exp_f32_e32 v146, v146
	v_exp_f32_e32 v147, v147
	v_pk_mul_f32 v[116:117], v[124:125], v[116:117]
	v_pk_mul_f32 v[118:119], v[126:127], v[118:119]
	v_pk_add_f32 v[144:145], v[144:145], 1.0 op_sel_hi:[1,0]
	v_pk_add_f32 v[146:147], v[146:147], 1.0 op_sel_hi:[1,0]
	v_rcp_f32_e32 v144, v144
	v_rcp_f32_e32 v145, v145
	v_rcp_f32_e32 v146, v146
	v_rcp_f32_e32 v147, v147
	v_pk_mul_f32 v[116:117], v[144:145], v[116:117]
	v_pk_mul_f32 v[118:119], v[146:147], v[118:119]
	v_cvt_pk_bf16_f32 v124, v116, v117
	v_cvt_pk_bf16_f32 v125, v118, v119
	v_pk_mul_f32 v[144:145], v[120:121], v[152:153]
	v_pk_mul_f32 v[146:147], v[122:123], v[152:153]
	v_exp_f32_e32 v144, v144
	v_exp_f32_e32 v145, v145
	v_exp_f32_e32 v146, v146
	v_exp_f32_e32 v147, v147
	v_pk_mul_f32 v[112:113], v[120:121], v[112:113]
	v_pk_mul_f32 v[114:115], v[122:123], v[114:115]
	v_pk_add_f32 v[144:145], v[144:145], 1.0 op_sel_hi:[1,0]
	v_pk_add_f32 v[146:147], v[146:147], 1.0 op_sel_hi:[1,0]
	v_rcp_f32_e32 v144, v144
	v_rcp_f32_e32 v145, v145
	v_rcp_f32_e32 v146, v146
	v_rcp_f32_e32 v147, v147
	v_pk_mul_f32 v[112:113], v[144:145], v[112:113]
	v_pk_mul_f32 v[114:115], v[146:147], v[114:115]
	v_cvt_pk_bf16_f32 v126, v112, v113
	v_cvt_pk_bf16_f32 v127, v114, v115
	global_store_dwordx4 v148, v[124:127], s[12:13]
	v_pk_mul_f32 v[144:145], v[108:109], v[152:153]
	v_pk_mul_f32 v[146:147], v[110:111], v[152:153]
	v_exp_f32_e32 v144, v144
	v_exp_f32_e32 v145, v145
	v_exp_f32_e32 v146, v146
	v_exp_f32_e32 v147, v147
	v_pk_mul_f32 v[100:101], v[108:109], v[100:101]
	v_pk_mul_f32 v[102:103], v[110:111], v[102:103]
	v_pk_add_f32 v[144:145], v[144:145], 1.0 op_sel_hi:[1,0]
	v_pk_add_f32 v[146:147], v[146:147], 1.0 op_sel_hi:[1,0]
	v_rcp_f32_e32 v144, v144
	v_rcp_f32_e32 v145, v145
	v_rcp_f32_e32 v146, v146
	v_rcp_f32_e32 v147, v147
	v_pk_mul_f32 v[100:101], v[144:145], v[100:101]
	v_pk_mul_f32 v[102:103], v[146:147], v[102:103]
	v_cvt_pk_bf16_f32 v108, v100, v101
	v_cvt_pk_bf16_f32 v109, v102, v103
	v_pk_mul_f32 v[144:145], v[104:105], v[152:153]
	v_pk_mul_f32 v[146:147], v[106:107], v[152:153]
	v_exp_f32_e32 v144, v144
	v_exp_f32_e32 v145, v145
	v_exp_f32_e32 v146, v146
	v_exp_f32_e32 v147, v147
	v_pk_mul_f32 v[96:97], v[104:105], v[96:97]
	v_pk_mul_f32 v[98:99], v[106:107], v[98:99]
	v_pk_add_f32 v[144:145], v[144:145], 1.0 op_sel_hi:[1,0]
	v_pk_add_f32 v[146:147], v[146:147], 1.0 op_sel_hi:[1,0]
	v_rcp_f32_e32 v144, v144
	v_rcp_f32_e32 v145, v145
	v_rcp_f32_e32 v146, v146
	v_rcp_f32_e32 v147, v147
	v_pk_mul_f32 v[96:97], v[144:145], v[96:97]
	v_pk_mul_f32 v[98:99], v[146:147], v[98:99]
	v_cvt_pk_bf16_f32 v110, v96, v97
	v_cvt_pk_bf16_f32 v111, v98, v99
	v_add_u32_e32 v150, 0x16000, v148
	global_store_dwordx4 v150, v[108:111], s[12:13]
	v_pk_mul_f32 v[144:145], v[92:93], v[152:153]
	v_pk_mul_f32 v[146:147], v[94:95], v[152:153]
	v_exp_f32_e32 v144, v144
	v_exp_f32_e32 v145, v145
	v_exp_f32_e32 v146, v146
	v_exp_f32_e32 v147, v147
	v_pk_mul_f32 v[84:85], v[92:93], v[84:85]
	v_pk_mul_f32 v[86:87], v[94:95], v[86:87]
	v_pk_add_f32 v[144:145], v[144:145], 1.0 op_sel_hi:[1,0]
	v_pk_add_f32 v[146:147], v[146:147], 1.0 op_sel_hi:[1,0]
	v_rcp_f32_e32 v144, v144
	v_rcp_f32_e32 v145, v145
	v_rcp_f32_e32 v146, v146
	v_rcp_f32_e32 v147, v147
	v_pk_mul_f32 v[84:85], v[144:145], v[84:85]
	v_pk_mul_f32 v[86:87], v[146:147], v[86:87]
	v_cvt_pk_bf16_f32 v92, v84, v85
	v_cvt_pk_bf16_f32 v93, v86, v87
	v_pk_mul_f32 v[144:145], v[88:89], v[152:153]
	v_pk_mul_f32 v[146:147], v[90:91], v[152:153]
	v_exp_f32_e32 v144, v144
	v_exp_f32_e32 v145, v145
	v_exp_f32_e32 v146, v146
	v_exp_f32_e32 v147, v147
	v_pk_mul_f32 v[80:81], v[88:89], v[80:81]
	v_pk_mul_f32 v[82:83], v[90:91], v[82:83]
	v_pk_add_f32 v[144:145], v[144:145], 1.0 op_sel_hi:[1,0]
	v_pk_add_f32 v[146:147], v[146:147], 1.0 op_sel_hi:[1,0]
	v_rcp_f32_e32 v144, v144
	v_rcp_f32_e32 v145, v145
	v_rcp_f32_e32 v146, v146
	v_rcp_f32_e32 v147, v147
	v_pk_mul_f32 v[80:81], v[144:145], v[80:81]
	v_pk_mul_f32 v[82:83], v[146:147], v[82:83]
	v_cvt_pk_bf16_f32 v94, v80, v81
	v_cvt_pk_bf16_f32 v95, v82, v83
	v_add_u32_e32 v150, 0x2c000, v148
	global_store_dwordx4 v150, v[92:95], s[12:13]
	v_pk_mul_f32 v[144:145], v[76:77], v[152:153]
	v_pk_mul_f32 v[146:147], v[78:79], v[152:153]
	v_exp_f32_e32 v144, v144
	v_exp_f32_e32 v145, v145
	v_exp_f32_e32 v146, v146
	v_exp_f32_e32 v147, v147
	v_pk_mul_f32 v[68:69], v[76:77], v[68:69]
	v_pk_mul_f32 v[70:71], v[78:79], v[70:71]
	v_pk_add_f32 v[144:145], v[144:145], 1.0 op_sel_hi:[1,0]
	v_pk_add_f32 v[146:147], v[146:147], 1.0 op_sel_hi:[1,0]
	v_rcp_f32_e32 v144, v144
	v_rcp_f32_e32 v145, v145
	v_rcp_f32_e32 v146, v146
	v_rcp_f32_e32 v147, v147
	v_pk_mul_f32 v[68:69], v[144:145], v[68:69]
	v_pk_mul_f32 v[70:71], v[146:147], v[70:71]
	v_cvt_pk_bf16_f32 v76, v68, v69
	v_cvt_pk_bf16_f32 v77, v70, v71
	v_pk_mul_f32 v[144:145], v[72:73], v[152:153]
	v_pk_mul_f32 v[146:147], v[74:75], v[152:153]
	v_exp_f32_e32 v144, v144
	v_exp_f32_e32 v145, v145
	v_exp_f32_e32 v146, v146
	v_exp_f32_e32 v147, v147
	v_pk_mul_f32 v[64:65], v[72:73], v[64:65]
	v_pk_mul_f32 v[66:67], v[74:75], v[66:67]
	v_pk_add_f32 v[144:145], v[144:145], 1.0 op_sel_hi:[1,0]
	v_pk_add_f32 v[146:147], v[146:147], 1.0 op_sel_hi:[1,0]
; __device__ __forceinline__ float ex2(float x) { return __builtin_amdgcn_exp2f(x); }
; __device__ __forceinline__ u32x4 pack8(const f32x4 a, const f32x4 b) { u32x4 w; w.x = pk2(a[0], a[1]); w.y = pk2(a[2], a[3]); w.z = pk2(b[0], b[1]); w.w = pk2(b[2], b[3]); return w; }
;     __device__ __forceinline__ bool operator()(EPI_ARGS) const {
;     ...
;                 const size_t row = (size_t)u.pm * 256 + ROWLOC(ai, m);
;                 const f32x4 a0 = acc[ai][0][m][0], a1 = acc[ai][0][m][1], b0 = acc[ai][1][m][0], b1 = acc[ai][1][m][1];
;                 const f32x4 t0 = a0 * (-1.4426950409f), t1 = a1 * (-1.4426950409f);
;                 f32x4 d0, d1;
; #pragma unroll
;                 for (int e = 0; e < 4; ++e) { d0[e] = ex2(t0[e]); d1[e] = ex2(t1[e]); }
;                 d0 = d0 + 1.0f; d1 = d1 + 1.0f;
;                 f32x4 r0, r1;
; #pragma unroll
;                 for (int e = 0; e < 4; ++e) { r0[e] = __builtin_amdgcn_rcpf(d0[e]); r1[e] = __builtin_amdgcn_rcpf(d1[e]); }
;                 const f32x4 o0 = (a0 * b0) * r0, o1 = (a1 * b1) * r1;
;                 *(u32x4*)(act + row * DFF + u.pn * 128 + 32 * wc + 8 * fq) = pack8(o0, o1);
;             }
;         return false;
	v_rcp_f32_e32 v144, v144
	v_rcp_f32_e32 v145, v145
	v_rcp_f32_e32 v146, v146
	v_rcp_f32_e32 v147, v147
	v_pk_mul_f32 v[64:65], v[144:145], v[64:65]
	v_pk_mul_f32 v[66:67], v[146:147], v[66:67]
	v_cvt_pk_bf16_f32 v78, v64, v65
	v_cvt_pk_bf16_f32 v79, v66, v67
	v_add_u32_e32 v150, 0x42000, v148
	global_store_dwordx4 v150, v[76:79], s[12:13]
	v_pk_mul_f32 v[144:145], v[60:61], v[152:153]
	v_pk_mul_f32 v[146:147], v[62:63], v[152:153]
	v_exp_f32_e32 v144, v144
	v_exp_f32_e32 v145, v145
	v_exp_f32_e32 v146, v146
	v_exp_f32_e32 v147, v147
	v_pk_mul_f32 v[52:53], v[60:61], v[52:53]
	v_pk_mul_f32 v[54:55], v[62:63], v[54:55]
	v_pk_add_f32 v[144:145], v[144:145], 1.0 op_sel_hi:[1,0]
	v_pk_add_f32 v[146:147], v[146:147], 1.0 op_sel_hi:[1,0]
	v_rcp_f32_e32 v144, v144
	v_rcp_f32_e32 v145, v145
	v_rcp_f32_e32 v146, v146
	v_rcp_f32_e32 v147, v147
	v_pk_mul_f32 v[52:53], v[144:145], v[52:53]
	v_pk_mul_f32 v[54:55], v[146:147], v[54:55]
	v_cvt_pk_bf16_f32 v60, v52, v53
	v_cvt_pk_bf16_f32 v61, v54, v55
	v_pk_mul_f32 v[144:145], v[56:57], v[152:153]
	v_pk_mul_f32 v[146:147], v[58:59], v[152:153]
	v_exp_f32_e32 v144, v144
	v_exp_f32_e32 v145, v145
	v_exp_f32_e32 v146, v146
	v_exp_f32_e32 v147, v147
	v_pk_mul_f32 v[48:49], v[56:57], v[48:49]
	v_pk_mul_f32 v[50:51], v[58:59], v[50:51]
	v_pk_add_f32 v[144:145], v[144:145], 1.0 op_sel_hi:[1,0]
	v_pk_add_f32 v[146:147], v[146:147], 1.0 op_sel_hi:[1,0]
	v_rcp_f32_e32 v144, v144
	v_rcp_f32_e32 v145, v145
	v_rcp_f32_e32 v146, v146
	v_rcp_f32_e32 v147, v147
	v_pk_mul_f32 v[48:49], v[144:145], v[48:49]
	v_pk_mul_f32 v[50:51], v[146:147], v[50:51]
	v_cvt_pk_bf16_f32 v62, v48, v49
	v_cvt_pk_bf16_f32 v63, v50, v51
	v_add_u32_e32 v150, 0xb0000, v148
	global_store_dwordx4 v150, v[60:63], s[12:13]
	v_pk_mul_f32 v[144:145], v[44:45], v[152:153]
	v_pk_mul_f32 v[146:147], v[46:47], v[152:153]
	v_exp_f32_e32 v144, v144
	v_exp_f32_e32 v145, v145
	v_exp_f32_e32 v146, v146
	v_exp_f32_e32 v147, v147
	v_pk_mul_f32 v[36:37], v[44:45], v[36:37]
	v_pk_mul_f32 v[38:39], v[46:47], v[38:39]
	v_pk_add_f32 v[144:145], v[144:145], 1.0 op_sel_hi:[1,0]
	v_pk_add_f32 v[146:147], v[146:147], 1.0 op_sel_hi:[1,0]
	v_rcp_f32_e32 v144, v144
	v_rcp_f32_e32 v145, v145
	v_rcp_f32_e32 v146, v146
	v_rcp_f32_e32 v147, v147
	v_pk_mul_f32 v[36:37], v[144:145], v[36:37]
	v_pk_mul_f32 v[38:39], v[146:147], v[38:39]
	v_cvt_pk_bf16_f32 v44, v36, v37
	v_cvt_pk_bf16_f32 v45, v38, v39
	v_pk_mul_f32 v[144:145], v[40:41], v[152:153]
	v_pk_mul_f32 v[146:147], v[42:43], v[152:153]
	v_exp_f32_e32 v144, v144
	v_exp_f32_e32 v145, v145
	v_exp_f32_e32 v146, v146
	v_exp_f32_e32 v147, v147
	v_pk_mul_f32 v[32:33], v[40:41], v[32:33]
	v_pk_mul_f32 v[34:35], v[42:43], v[34:35]
	v_pk_add_f32 v[144:145], v[144:145], 1.0 op_sel_hi:[1,0]
	v_pk_add_f32 v[146:147], v[146:147], 1.0 op_sel_hi:[1,0]
	v_rcp_f32_e32 v144, v144
	v_rcp_f32_e32 v145, v145
	v_rcp_f32_e32 v146, v146
	v_rcp_f32_e32 v147, v147
	v_pk_mul_f32 v[32:33], v[144:145], v[32:33]
	v_pk_mul_f32 v[34:35], v[146:147], v[34:35]
	v_cvt_pk_bf16_f32 v46, v32, v33
	v_cvt_pk_bf16_f32 v47, v34, v35
	v_add_u32_e32 v150, 0xc6000, v148
	global_store_dwordx4 v150, v[44:47], s[12:13]
	v_pk_mul_f32 v[144:145], v[28:29], v[152:153]
	v_pk_mul_f32 v[146:147], v[30:31], v[152:153]
	v_exp_f32_e32 v144, v144
	v_exp_f32_e32 v145, v145
	v_exp_f32_e32 v146, v146
	v_exp_f32_e32 v147, v147
	v_pk_mul_f32 v[20:21], v[28:29], v[20:21]
	v_pk_mul_f32 v[22:23], v[30:31], v[22:23]
	v_pk_add_f32 v[144:145], v[144:145], 1.0 op_sel_hi:[1,0]
	v_pk_add_f32 v[146:147], v[146:147], 1.0 op_sel_hi:[1,0]
	v_rcp_f32_e32 v144, v144
	v_rcp_f32_e32 v145, v145
	v_rcp_f32_e32 v146, v146
	v_rcp_f32_e32 v147, v147
	v_pk_mul_f32 v[20:21], v[144:145], v[20:21]
	v_pk_mul_f32 v[22:23], v[146:147], v[22:23]
	v_cvt_pk_bf16_f32 v28, v20, v21
	v_cvt_pk_bf16_f32 v29, v22, v23
	v_pk_mul_f32 v[144:145], v[24:25], v[152:153]
	v_pk_mul_f32 v[146:147], v[26:27], v[152:153]
	v_exp_f32_e32 v144, v144
	v_exp_f32_e32 v145, v145
	v_exp_f32_e32 v146, v146
	v_exp_f32_e32 v147, v147
	v_pk_mul_f32 v[16:17], v[24:25], v[16:17]
	v_pk_mul_f32 v[18:19], v[26:27], v[18:19]
	v_pk_add_f32 v[144:145], v[144:145], 1.0 op_sel_hi:[1,0]
	v_pk_add_f32 v[146:147], v[146:147], 1.0 op_sel_hi:[1,0]
	v_rcp_f32_e32 v144, v144
	v_rcp_f32_e32 v145, v145
	v_rcp_f32_e32 v146, v146
	v_rcp_f32_e32 v147, v147
	v_pk_mul_f32 v[16:17], v[144:145], v[16:17]
	v_pk_mul_f32 v[18:19], v[146:147], v[18:19]
	v_cvt_pk_bf16_f32 v30, v16, v17
	v_cvt_pk_bf16_f32 v31, v18, v19
	v_add_u32_e32 v150, 0xdc000, v148
	global_store_dwordx4 v150, v[28:31], s[12:13]
	v_pk_mul_f32 v[144:145], v[12:13], v[152:153]
	v_pk_mul_f32 v[146:147], v[14:15], v[152:153]
	v_exp_f32_e32 v144, v144
	v_exp_f32_e32 v145, v145
	v_exp_f32_e32 v146, v146
	v_exp_f32_e32 v147, v147
	v_pk_mul_f32 v[4:5], v[12:13], v[4:5]
	v_pk_mul_f32 v[6:7], v[14:15], v[6:7]
	v_pk_add_f32 v[144:145], v[144:145], 1.0 op_sel_hi:[1,0]
	v_pk_add_f32 v[146:147], v[146:147], 1.0 op_sel_hi:[1,0]
	v_rcp_f32_e32 v144, v144
	v_rcp_f32_e32 v145, v145
	v_rcp_f32_e32 v146, v146
	v_rcp_f32_e32 v147, v147
	v_pk_mul_f32 v[4:5], v[144:145], v[4:5]
	v_pk_mul_f32 v[6:7], v[146:147], v[6:7]
	v_cvt_pk_bf16_f32 v12, v4, v5
	v_cvt_pk_bf16_f32 v13, v6, v7
	v_pk_mul_f32 v[144:145], v[8:9], v[152:153]
	v_pk_mul_f32 v[146:147], v[10:11], v[152:153]
	v_exp_f32_e32 v144, v144
	v_exp_f32_e32 v145, v145
	v_exp_f32_e32 v146, v146
	v_exp_f32_e32 v147, v147
	v_pk_mul_f32 v[0:1], v[8:9], v[0:1]
	v_pk_mul_f32 v[2:3], v[10:11], v[2:3]
	v_pk_add_f32 v[144:145], v[144:145], 1.0 op_sel_hi:[1,0]
	v_pk_add_f32 v[146:147], v[146:147], 1.0 op_sel_hi:[1,0]
	v_rcp_f32_e32 v144, v144
	v_rcp_f32_e32 v145, v145
	v_rcp_f32_e32 v146, v146
	v_rcp_f32_e32 v147, v147
	v_pk_mul_f32 v[0:1], v[144:145], v[0:1]
	v_pk_mul_f32 v[2:3], v[146:147], v[2:3]
	v_cvt_pk_bf16_f32 v14, v0, v1
	v_cvt_pk_bf16_f32 v15, v2, v3
	v_add_u32_e32 v150, 0xf2000, v148
	global_store_dwordx4 v150, v[12:15], s[12:13]
	s_andn2_b64 vcc, exec, s[8:9]
	s_mov_b64 s[8:9], -1
	s_cbranch_vccnz .LBB0_1481
	s_andn2_b64 vcc, exec, s[10:11]
	s_cbranch_vccnz .LBB0_1480
	s_barrier
	s_branch .LBB0_1480
